# C/E K-loop: 16 more LDS-DMA address adds moved to SALU+saddr (temp pair s[100:101])
# baseline (speedup 1.0000x reference)
.LBB0_195:
	s_add_u32 s42, s78, 0x80
	s_addc_u32 s43, s79, 0
	s_add_u32 s33, s44, 0x100
	s_addc_u32 s37, s45, 0
	s_mov_b32 s27, 0
	s_waitcnt lgkmcnt(0)
	s_add_i32 s56, s27, 2
	s_add_u32 s44, s42, 0x80
	s_addc_u32 s45, s43, 0
	s_add_i32 s57, 0, 0x10000
	ds_read_b128 v[128:131], v207
	ds_read_b128 v[132:135], v207 offset:1024
	ds_read_b128 v[136:139], v207 offset:2048
	ds_read_b128 v[140:143], v207 offset:3072
	s_cmp_eq_u32 s82, s27
	s_cselect_b32 s45, s77, s45
	s_cselect_b32 s44, s76, s44
	s_cselect_b32 s79, s1, s37
	s_cselect_b32 s78, s0, s33
	v_lshl_add_u64 v[176:177], s[42:43], 0, v[190:191]
	s_add_i32 m0, s85, 0xc000
	ds_read_b128 v[146:149], v217
	ds_read_b128 v[150:153], v217 offset:1024
	ds_read_b128 v[154:157], v217 offset:2048
	ds_read_b128 v[158:161], v217 offset:3072
	ds_read_b128 v[162:165], v217 offset:4096
	ds_read_b128 v[166:169], v217 offset:5120
	ds_read_b128 v[194:197], v217 offset:6144
	ds_read_b128 v[198:201], v217 offset:7168
	global_load_lds_dwordx4 v[176:177], off
	v_lshl_add_u64 v[176:177], s[42:43], 0, v[192:193]
	s_add_i32 m0, s85, 0xe000
	s_nop 0
	global_load_lds_dwordx4 v[176:177], off
	s_waitcnt lgkmcnt(8)
	s_barrier
	s_waitcnt lgkmcnt(0)
	v_mfma_f32_16x16x32_bf16 v[124:127], v[128:131], v[146:149], 0
	v_mfma_f32_16x16x32_bf16 v[120:123], v[136:139], v[146:149], 0
	v_mfma_f32_16x16x32_bf16 v[108:111], v[128:131], v[154:157], 0
	v_mfma_f32_16x16x32_bf16 v[104:107], v[136:139], v[154:157], 0
	v_mfma_f32_16x16x32_bf16 v[92:95], v[128:131], v[162:165], 0
	v_mfma_f32_16x16x32_bf16 v[88:91], v[136:139], v[162:165], 0
	v_mfma_f32_16x16x32_bf16 v[76:79], v[128:131], v[194:197], 0
	v_mfma_f32_16x16x32_bf16 v[72:75], v[136:139], v[194:197], 0
	v_mfma_f32_16x16x32_bf16 v[124:127], v[132:135], v[150:153], v[124:127]
	v_mfma_f32_16x16x32_bf16 v[120:123], v[140:143], v[150:153], v[120:123]
	v_mfma_f32_16x16x32_bf16 v[108:111], v[132:135], v[158:161], v[108:111]
	v_mfma_f32_16x16x32_bf16 v[104:107], v[140:143], v[158:161], v[104:107]
	v_mfma_f32_16x16x32_bf16 v[92:95], v[132:135], v[166:169], v[92:95]
	v_mfma_f32_16x16x32_bf16 v[88:91], v[140:143], v[166:169], v[88:91]
	v_mfma_f32_16x16x32_bf16 v[76:79], v[132:135], v[198:201], v[76:79]
	v_mfma_f32_16x16x32_bf16 v[72:75], v[140:143], v[198:201], v[72:75]
	s_barrier
	s_add_i32 s27, 0, 0x14000
	s_add_i32 s57, s57, s84
	ds_read_b128 v[202:205], v207 offset:16384
	ds_read_b128 v[218:221], v207 offset:17408
	ds_read_b128 v[222:225], v207 offset:18432
	ds_read_b128 v[228:231], v207 offset:19456
	s_mov_b32 m0, s57
	global_load_lds_dwordx4 v144, s[78:79]
	s_add_i32 m0, s57, 0x2000
	s_nop 0
	global_load_lds_dwordx4 v188, s[78:79]
	s_barrier
	s_waitcnt lgkmcnt(0)
	v_mfma_f32_16x16x32_bf16 v[116:119], v[202:205], v[146:149], 0
	v_mfma_f32_16x16x32_bf16 v[112:115], v[222:225], v[146:149], 0
	v_mfma_f32_16x16x32_bf16 v[100:103], v[202:205], v[154:157], 0
	v_mfma_f32_16x16x32_bf16 v[96:99], v[222:225], v[154:157], 0
	v_mfma_f32_16x16x32_bf16 v[84:87], v[202:205], v[162:165], 0
	v_mfma_f32_16x16x32_bf16 v[80:83], v[222:225], v[162:165], 0
	v_mfma_f32_16x16x32_bf16 v[68:71], v[202:205], v[194:197], 0
	v_mfma_f32_16x16x32_bf16 v[64:67], v[222:225], v[194:197], 0
	v_mfma_f32_16x16x32_bf16 v[116:119], v[218:221], v[150:153], v[116:119]
	v_mfma_f32_16x16x32_bf16 v[112:115], v[228:231], v[150:153], v[112:115]
	v_mfma_f32_16x16x32_bf16 v[100:103], v[218:221], v[158:161], v[100:103]
	v_mfma_f32_16x16x32_bf16 v[96:99], v[228:231], v[158:161], v[96:99]
	v_mfma_f32_16x16x32_bf16 v[84:87], v[218:221], v[166:169], v[84:87]
	v_mfma_f32_16x16x32_bf16 v[80:83], v[228:231], v[166:169], v[80:83]
	v_mfma_f32_16x16x32_bf16 v[68:71], v[218:221], v[198:201], v[68:71]
	v_mfma_f32_16x16x32_bf16 v[64:67], v[228:231], v[198:201], v[64:67]
	s_barrier
	s_mov_b32 m0, s85
	v_lshl_add_u64 v[234:235], s[44:45], 0, v[144:145]
	ds_read_b128 v[146:149], v217 offset:16384
	ds_read_b128 v[150:153], v217 offset:17408
	ds_read_b128 v[154:157], v217 offset:18432
	ds_read_b128 v[158:161], v217 offset:19456
	ds_read_b128 v[162:165], v217 offset:20480
	ds_read_b128 v[166:169], v217 offset:21504
	ds_read_b128 v[194:197], v217 offset:22528
	ds_read_b128 v[198:201], v217 offset:23552
	global_load_lds_dwordx4 v[234:235], off
	v_lshl_add_u64 v[236:237], s[44:45], 0, v[188:189]
	s_mov_b32 m0, s86
	s_nop 0
	global_load_lds_dwordx4 v[236:237], off
	s_barrier
	s_waitcnt lgkmcnt(0)
	v_mfma_f32_16x16x32_bf16 v[60:63], v[128:131], v[146:149], 0
	v_mfma_f32_16x16x32_bf16 v[56:59], v[136:139], v[146:149], 0
	v_mfma_f32_16x16x32_bf16 v[44:47], v[128:131], v[154:157], 0
	v_mfma_f32_16x16x32_bf16 v[40:43], v[136:139], v[154:157], 0
	v_mfma_f32_16x16x32_bf16 v[28:31], v[128:131], v[162:165], 0
	v_mfma_f32_16x16x32_bf16 v[24:27], v[136:139], v[162:165], 0
	v_mfma_f32_16x16x32_bf16 v[12:15], v[128:131], v[194:197], 0
	v_mfma_f32_16x16x32_bf16 v[8:11], v[136:139], v[194:197], 0
	v_mfma_f32_16x16x32_bf16 v[60:63], v[132:135], v[150:153], v[60:63]
	v_mfma_f32_16x16x32_bf16 v[56:59], v[140:143], v[150:153], v[56:59]
	v_mfma_f32_16x16x32_bf16 v[44:47], v[132:135], v[158:161], v[44:47]
	v_mfma_f32_16x16x32_bf16 v[40:43], v[140:143], v[158:161], v[40:43]
	v_mfma_f32_16x16x32_bf16 v[28:31], v[132:135], v[166:169], v[28:31]
	v_mfma_f32_16x16x32_bf16 v[24:27], v[140:143], v[166:169], v[24:27]
	v_mfma_f32_16x16x32_bf16 v[12:15], v[132:135], v[198:201], v[12:15]
	v_mfma_f32_16x16x32_bf16 v[8:11], v[140:143], v[198:201], v[8:11]
	s_barrier
	s_add_u32 s58, s78, s98
	s_addc_u32 s59, s79, 0
	s_add_i32 s27, s27, s84
	s_mov_b32 m0, s27
	global_load_lds_dwordx4 v144, s[58:59]
	s_add_i32 m0, s27, 0x2000
	s_nop 0
	global_load_lds_dwordx4 v188, s[58:59]
	s_waitcnt vmcnt(6)
	s_barrier
	v_mfma_f32_16x16x32_bf16 v[52:55], v[202:205], v[146:149], 0
	v_mfma_f32_16x16x32_bf16 v[48:51], v[222:225], v[146:149], 0
	v_mfma_f32_16x16x32_bf16 v[36:39], v[202:205], v[154:157], 0
	v_mfma_f32_16x16x32_bf16 v[32:35], v[222:225], v[154:157], 0
	v_mfma_f32_16x16x32_bf16 v[20:23], v[202:205], v[162:165], 0
	v_mfma_f32_16x16x32_bf16 v[16:19], v[222:225], v[162:165], 0
	v_mfma_f32_16x16x32_bf16 v[4:7], v[202:205], v[194:197], 0
	v_mfma_f32_16x16x32_bf16 v[0:3], v[222:225], v[194:197], 0
	v_mfma_f32_16x16x32_bf16 v[52:55], v[218:221], v[150:153], v[52:55]
	v_mfma_f32_16x16x32_bf16 v[48:51], v[228:231], v[150:153], v[48:51]
	v_mfma_f32_16x16x32_bf16 v[36:39], v[218:221], v[158:161], v[36:39]
	v_mfma_f32_16x16x32_bf16 v[32:35], v[228:231], v[158:161], v[32:35]
	v_mfma_f32_16x16x32_bf16 v[20:23], v[218:221], v[166:169], v[20:23]
	v_mfma_f32_16x16x32_bf16 v[16:19], v[228:231], v[166:169], v[16:19]
	v_mfma_f32_16x16x32_bf16 v[4:7], v[218:221], v[198:201], v[4:7]
	v_mfma_f32_16x16x32_bf16 v[0:3], v[228:231], v[198:201], v[0:3]
	s_barrier
	s_add_i32 s27, 0, 0x18000
	ds_read_b128 v[128:131], v207 offset:32768
	ds_read_b128 v[132:135], v207 offset:33792
	ds_read_b128 v[136:139], v207 offset:34816
	ds_read_b128 v[140:143], v207 offset:35840
	s_add_u32 s44, s44, s98
	s_addc_u32 s45, s45, 0
	s_mov_b32 m0, s87
	ds_read_b128 v[146:149], v217 offset:32768
	ds_read_b128 v[150:153], v217 offset:33792
	ds_read_b128 v[154:157], v217 offset:34816
	ds_read_b128 v[158:161], v217 offset:35840
	ds_read_b128 v[162:165], v217 offset:36864
	ds_read_b128 v[166:169], v217 offset:37888
	ds_read_b128 v[194:197], v217 offset:38912
	ds_read_b128 v[198:201], v217 offset:39936
	global_load_lds_dwordx4 v144, s[44:45]
	s_mov_b32 m0, s80
	s_nop 0
	global_load_lds_dwordx4 v188, s[44:45]
	s_waitcnt lgkmcnt(8)
	s_barrier
	s_waitcnt lgkmcnt(0)
	v_mfma_f32_16x16x32_bf16 v[124:127], v[128:131], v[146:149], v[124:127]
	v_mfma_f32_16x16x32_bf16 v[120:123], v[136:139], v[146:149], v[120:123]
	v_mfma_f32_16x16x32_bf16 v[108:111], v[128:131], v[154:157], v[108:111]
	v_mfma_f32_16x16x32_bf16 v[104:107], v[136:139], v[154:157], v[104:107]
	v_mfma_f32_16x16x32_bf16 v[92:95], v[128:131], v[162:165], v[92:95]
	v_mfma_f32_16x16x32_bf16 v[88:91], v[136:139], v[162:165], v[88:91]
	v_mfma_f32_16x16x32_bf16 v[76:79], v[128:131], v[194:197], v[76:79]
	v_mfma_f32_16x16x32_bf16 v[72:75], v[136:139], v[194:197], v[72:75]
	v_mfma_f32_16x16x32_bf16 v[124:127], v[132:135], v[150:153], v[124:127]
	v_mfma_f32_16x16x32_bf16 v[120:123], v[140:143], v[150:153], v[120:123]
	v_mfma_f32_16x16x32_bf16 v[108:111], v[132:135], v[158:161], v[108:111]
	v_mfma_f32_16x16x32_bf16 v[104:107], v[140:143], v[158:161], v[104:107]
	v_mfma_f32_16x16x32_bf16 v[92:95], v[132:135], v[166:169], v[92:95]
	v_mfma_f32_16x16x32_bf16 v[88:91], v[140:143], v[166:169], v[88:91]
	v_mfma_f32_16x16x32_bf16 v[76:79], v[132:135], v[198:201], v[76:79]
	v_mfma_f32_16x16x32_bf16 v[72:75], v[140:143], v[198:201], v[72:75]
	s_barrier
	s_add_i32 s44, 0, 0x1c000
	s_add_i32 s27, s27, s84
	s_add_u32 s100, s78, s18
	s_addc_u32 s101, s79, s19
	s_mov_b32 m0, s27
	ds_read_b128 v[202:205], v207 offset:49152
	ds_read_b128 v[218:221], v207 offset:50176
	ds_read_b128 v[222:225], v207 offset:51200
	ds_read_b128 v[228:231], v207 offset:52224
	global_load_lds_dwordx4 v144, s[100:101]
	s_add_u32 s100, s78, s18
	s_addc_u32 s101, s79, s19
	s_add_i32 m0, s27, 0x2000
	s_nop 0
	global_load_lds_dwordx4 v188, s[100:101]
	s_barrier
	s_waitcnt lgkmcnt(0)
	v_mfma_f32_16x16x32_bf16 v[116:119], v[202:205], v[146:149], v[116:119]
	v_mfma_f32_16x16x32_bf16 v[112:115], v[222:225], v[146:149], v[112:115]
	v_mfma_f32_16x16x32_bf16 v[100:103], v[202:205], v[154:157], v[100:103]
	v_mfma_f32_16x16x32_bf16 v[96:99], v[222:225], v[154:157], v[96:99]
	v_mfma_f32_16x16x32_bf16 v[84:87], v[202:205], v[162:165], v[84:87]
	v_mfma_f32_16x16x32_bf16 v[80:83], v[222:225], v[162:165], v[80:83]
	v_mfma_f32_16x16x32_bf16 v[68:71], v[202:205], v[194:197], v[68:71]
	v_mfma_f32_16x16x32_bf16 v[64:67], v[222:225], v[194:197], v[64:67]
	v_mfma_f32_16x16x32_bf16 v[116:119], v[218:221], v[150:153], v[116:119]
	v_mfma_f32_16x16x32_bf16 v[112:115], v[228:231], v[150:153], v[112:115]
	v_mfma_f32_16x16x32_bf16 v[100:103], v[218:221], v[158:161], v[100:103]
	v_mfma_f32_16x16x32_bf16 v[96:99], v[228:231], v[158:161], v[96:99]
	v_mfma_f32_16x16x32_bf16 v[84:87], v[218:221], v[166:169], v[84:87]
	v_mfma_f32_16x16x32_bf16 v[80:83], v[228:231], v[166:169], v[80:83]
	v_mfma_f32_16x16x32_bf16 v[68:71], v[218:221], v[198:201], v[68:71]
	v_mfma_f32_16x16x32_bf16 v[64:67], v[228:231], v[198:201], v[64:67]
	s_barrier
	s_mov_b32 m0, s30
	v_lshl_add_u64 v[176:177], v[234:235], 0, s[18:19]
	ds_read_b128 v[146:149], v217 offset:49152
	ds_read_b128 v[150:153], v217 offset:50176
	ds_read_b128 v[154:157], v217 offset:51200
	ds_read_b128 v[158:161], v217 offset:52224
	ds_read_b128 v[162:165], v217 offset:53248
	ds_read_b128 v[166:169], v217 offset:54272
	ds_read_b128 v[194:197], v217 offset:55296
	ds_read_b128 v[198:201], v217 offset:56320
	global_load_lds_dwordx4 v[176:177], off
	v_lshl_add_u64 v[176:177], v[236:237], 0, s[18:19]
	s_mov_b32 m0, s31
	s_nop 0
	global_load_lds_dwordx4 v[176:177], off
	s_barrier
	s_waitcnt lgkmcnt(0)
	v_mfma_f32_16x16x32_bf16 v[60:63], v[128:131], v[146:149], v[60:63]
	v_mfma_f32_16x16x32_bf16 v[56:59], v[136:139], v[146:149], v[56:59]
	v_mfma_f32_16x16x32_bf16 v[44:47], v[128:131], v[154:157], v[44:47]
	v_mfma_f32_16x16x32_bf16 v[40:43], v[136:139], v[154:157], v[40:43]
	v_mfma_f32_16x16x32_bf16 v[28:31], v[128:131], v[162:165], v[28:31]
	v_mfma_f32_16x16x32_bf16 v[24:27], v[136:139], v[162:165], v[24:27]
	v_mfma_f32_16x16x32_bf16 v[12:15], v[128:131], v[194:197], v[12:15]
	v_mfma_f32_16x16x32_bf16 v[8:11], v[136:139], v[194:197], v[8:11]
	v_mfma_f32_16x16x32_bf16 v[60:63], v[132:135], v[150:153], v[60:63]
	v_mfma_f32_16x16x32_bf16 v[56:59], v[140:143], v[150:153], v[56:59]
	v_mfma_f32_16x16x32_bf16 v[44:47], v[132:135], v[158:161], v[44:47]
	v_mfma_f32_16x16x32_bf16 v[40:43], v[140:143], v[158:161], v[40:43]
	v_mfma_f32_16x16x32_bf16 v[28:31], v[132:135], v[166:169], v[28:31]
	v_mfma_f32_16x16x32_bf16 v[24:27], v[140:143], v[166:169], v[24:27]
	v_mfma_f32_16x16x32_bf16 v[12:15], v[132:135], v[198:201], v[12:15]
	v_mfma_f32_16x16x32_bf16 v[8:11], v[140:143], v[198:201], v[8:11]
	s_barrier
	s_add_i32 s27, s44, s84
	s_add_u32 s100, s58, s18
	s_addc_u32 s101, s59, s19
	s_mov_b32 m0, s27
	s_nop 0
	global_load_lds_dwordx4 v144, s[100:101]
	s_add_u32 s100, s58, s18
	s_addc_u32 s101, s59, s19
	s_add_i32 m0, s27, 0x2000
	s_nop 0
	global_load_lds_dwordx4 v188, s[100:101]
	s_waitcnt vmcnt(6)
	s_barrier
	v_mfma_f32_16x16x32_bf16 v[52:55], v[202:205], v[146:149], v[52:55]
	v_mfma_f32_16x16x32_bf16 v[48:51], v[222:225], v[146:149], v[48:51]
	v_mfma_f32_16x16x32_bf16 v[36:39], v[202:205], v[154:157], v[36:39]
	v_mfma_f32_16x16x32_bf16 v[32:35], v[222:225], v[154:157], v[32:35]
	v_mfma_f32_16x16x32_bf16 v[20:23], v[202:205], v[162:165], v[20:23]
	v_mfma_f32_16x16x32_bf16 v[16:19], v[222:225], v[162:165], v[16:19]
	v_mfma_f32_16x16x32_bf16 v[4:7], v[202:205], v[194:197], v[4:7]
	v_mfma_f32_16x16x32_bf16 v[0:3], v[222:225], v[194:197], v[0:3]
	v_mfma_f32_16x16x32_bf16 v[52:55], v[218:221], v[150:153], v[52:55]
	v_mfma_f32_16x16x32_bf16 v[48:51], v[228:231], v[150:153], v[48:51]
	v_mfma_f32_16x16x32_bf16 v[36:39], v[218:221], v[158:161], v[36:39]
	v_mfma_f32_16x16x32_bf16 v[32:35], v[228:231], v[158:161], v[32:35]
	v_mfma_f32_16x16x32_bf16 v[20:23], v[218:221], v[166:169], v[20:23]
	v_mfma_f32_16x16x32_bf16 v[16:19], v[228:231], v[166:169], v[16:19]
	v_mfma_f32_16x16x32_bf16 v[4:7], v[218:221], v[198:201], v[4:7]
	v_mfma_f32_16x16x32_bf16 v[0:3], v[228:231], v[198:201], v[0:3]
	s_barrier
	s_add_u32 s42, s42, 0x100
	s_addc_u32 s43, s43, 0
	s_add_u32 s33, s33, 0x100
	s_addc_u32 s37, s37, 0
	s_cmp_ge_u32 s56, s34
	s_mov_b32 s27, s56
.LBB0_196:
	s_add_i32 s56, s27, 2
	s_add_u32 s44, s42, 0x80
	s_addc_u32 s45, s43, 0
	s_add_i32 s57, 0, 0x10000
	ds_read_b128 v[128:131], v207
	ds_read_b128 v[132:135], v207 offset:1024
	ds_read_b128 v[136:139], v207 offset:2048
	ds_read_b128 v[140:143], v207 offset:3072
	s_cmp_eq_u32 s82, s27
	s_cselect_b32 s45, s77, s45
	s_cselect_b32 s44, s76, s44
	s_cselect_b32 s79, s1, s37
	s_cselect_b32 s78, s0, s33
	v_lshl_add_u64 v[176:177], s[42:43], 0, v[190:191]
	s_add_i32 m0, s85, 0xc000
	ds_read_b128 v[146:149], v217
	ds_read_b128 v[150:153], v217 offset:1024
	ds_read_b128 v[154:157], v217 offset:2048
	ds_read_b128 v[158:161], v217 offset:3072
	ds_read_b128 v[162:165], v217 offset:4096
	ds_read_b128 v[166:169], v217 offset:5120
	ds_read_b128 v[194:197], v217 offset:6144
	ds_read_b128 v[198:201], v217 offset:7168
	global_load_lds_dwordx4 v[176:177], off
	v_lshl_add_u64 v[176:177], s[42:43], 0, v[192:193]
	s_add_i32 m0, s85, 0xe000
	s_nop 0
	global_load_lds_dwordx4 v[176:177], off
	s_waitcnt lgkmcnt(8)
	s_barrier
	s_waitcnt lgkmcnt(0)
	v_mfma_f32_16x16x32_bf16 v[124:127], v[128:131], v[146:149], v[124:127]
	v_mfma_f32_16x16x32_bf16 v[120:123], v[136:139], v[146:149], v[120:123]
	v_mfma_f32_16x16x32_bf16 v[108:111], v[128:131], v[154:157], v[108:111]
	v_mfma_f32_16x16x32_bf16 v[104:107], v[136:139], v[154:157], v[104:107]
	v_mfma_f32_16x16x32_bf16 v[92:95], v[128:131], v[162:165], v[92:95]
	v_mfma_f32_16x16x32_bf16 v[88:91], v[136:139], v[162:165], v[88:91]
	v_mfma_f32_16x16x32_bf16 v[76:79], v[128:131], v[194:197], v[76:79]
	v_mfma_f32_16x16x32_bf16 v[72:75], v[136:139], v[194:197], v[72:75]
	v_mfma_f32_16x16x32_bf16 v[124:127], v[132:135], v[150:153], v[124:127]
	v_mfma_f32_16x16x32_bf16 v[120:123], v[140:143], v[150:153], v[120:123]
	v_mfma_f32_16x16x32_bf16 v[108:111], v[132:135], v[158:161], v[108:111]
	v_mfma_f32_16x16x32_bf16 v[104:107], v[140:143], v[158:161], v[104:107]
	v_mfma_f32_16x16x32_bf16 v[92:95], v[132:135], v[166:169], v[92:95]
	v_mfma_f32_16x16x32_bf16 v[88:91], v[140:143], v[166:169], v[88:91]
	v_mfma_f32_16x16x32_bf16 v[76:79], v[132:135], v[198:201], v[76:79]
	v_mfma_f32_16x16x32_bf16 v[72:75], v[140:143], v[198:201], v[72:75]
	s_barrier
	s_add_i32 s27, 0, 0x14000
	s_add_i32 s57, s57, s84
	ds_read_b128 v[202:205], v207 offset:16384
	ds_read_b128 v[218:221], v207 offset:17408
	ds_read_b128 v[222:225], v207 offset:18432
	ds_read_b128 v[228:231], v207 offset:19456
	s_mov_b32 m0, s57
	global_load_lds_dwordx4 v144, s[78:79]
	s_add_i32 m0, s57, 0x2000
	s_nop 0
	global_load_lds_dwordx4 v188, s[78:79]
	s_barrier
	s_waitcnt lgkmcnt(0)
	v_mfma_f32_16x16x32_bf16 v[116:119], v[202:205], v[146:149], v[116:119]
	v_mfma_f32_16x16x32_bf16 v[112:115], v[222:225], v[146:149], v[112:115]
	v_mfma_f32_16x16x32_bf16 v[100:103], v[202:205], v[154:157], v[100:103]
	v_mfma_f32_16x16x32_bf16 v[96:99], v[222:225], v[154:157], v[96:99]
	v_mfma_f32_16x16x32_bf16 v[84:87], v[202:205], v[162:165], v[84:87]
	v_mfma_f32_16x16x32_bf16 v[80:83], v[222:225], v[162:165], v[80:83]
	v_mfma_f32_16x16x32_bf16 v[68:71], v[202:205], v[194:197], v[68:71]
	v_mfma_f32_16x16x32_bf16 v[64:67], v[222:225], v[194:197], v[64:67]
	v_mfma_f32_16x16x32_bf16 v[116:119], v[218:221], v[150:153], v[116:119]
	v_mfma_f32_16x16x32_bf16 v[112:115], v[228:231], v[150:153], v[112:115]
	v_mfma_f32_16x16x32_bf16 v[100:103], v[218:221], v[158:161], v[100:103]
	v_mfma_f32_16x16x32_bf16 v[96:99], v[228:231], v[158:161], v[96:99]
	v_mfma_f32_16x16x32_bf16 v[84:87], v[218:221], v[166:169], v[84:87]
	v_mfma_f32_16x16x32_bf16 v[80:83], v[228:231], v[166:169], v[80:83]
	v_mfma_f32_16x16x32_bf16 v[68:71], v[218:221], v[198:201], v[68:71]
	v_mfma_f32_16x16x32_bf16 v[64:67], v[228:231], v[198:201], v[64:67]
	s_barrier
	s_mov_b32 m0, s85
	v_lshl_add_u64 v[234:235], s[44:45], 0, v[144:145]
	ds_read_b128 v[146:149], v217 offset:16384
	ds_read_b128 v[150:153], v217 offset:17408
	ds_read_b128 v[154:157], v217 offset:18432
	ds_read_b128 v[158:161], v217 offset:19456
	ds_read_b128 v[162:165], v217 offset:20480
	ds_read_b128 v[166:169], v217 offset:21504
	ds_read_b128 v[194:197], v217 offset:22528
	ds_read_b128 v[198:201], v217 offset:23552
	global_load_lds_dwordx4 v[234:235], off
	v_lshl_add_u64 v[236:237], s[44:45], 0, v[188:189]
	s_mov_b32 m0, s86
	s_nop 0
	global_load_lds_dwordx4 v[236:237], off
	s_barrier
	s_waitcnt lgkmcnt(0)
	v_mfma_f32_16x16x32_bf16 v[60:63], v[128:131], v[146:149], v[60:63]
	v_mfma_f32_16x16x32_bf16 v[56:59], v[136:139], v[146:149], v[56:59]
	v_mfma_f32_16x16x32_bf16 v[44:47], v[128:131], v[154:157], v[44:47]
	v_mfma_f32_16x16x32_bf16 v[40:43], v[136:139], v[154:157], v[40:43]
	v_mfma_f32_16x16x32_bf16 v[28:31], v[128:131], v[162:165], v[28:31]
	v_mfma_f32_16x16x32_bf16 v[24:27], v[136:139], v[162:165], v[24:27]
	v_mfma_f32_16x16x32_bf16 v[12:15], v[128:131], v[194:197], v[12:15]
	v_mfma_f32_16x16x32_bf16 v[8:11], v[136:139], v[194:197], v[8:11]
	v_mfma_f32_16x16x32_bf16 v[60:63], v[132:135], v[150:153], v[60:63]
	v_mfma_f32_16x16x32_bf16 v[56:59], v[140:143], v[150:153], v[56:59]
	v_mfma_f32_16x16x32_bf16 v[44:47], v[132:135], v[158:161], v[44:47]
	v_mfma_f32_16x16x32_bf16 v[40:43], v[140:143], v[158:161], v[40:43]
	v_mfma_f32_16x16x32_bf16 v[28:31], v[132:135], v[166:169], v[28:31]
	v_mfma_f32_16x16x32_bf16 v[24:27], v[140:143], v[166:169], v[24:27]
	v_mfma_f32_16x16x32_bf16 v[12:15], v[132:135], v[198:201], v[12:15]
	v_mfma_f32_16x16x32_bf16 v[8:11], v[140:143], v[198:201], v[8:11]
	s_barrier
	s_add_u32 s58, s78, s98
	s_addc_u32 s59, s79, 0
	s_add_i32 s27, s27, s84
	s_mov_b32 m0, s27
	global_load_lds_dwordx4 v144, s[58:59]
	s_add_i32 m0, s27, 0x2000
	s_nop 0
	global_load_lds_dwordx4 v188, s[58:59]
	s_waitcnt vmcnt(6)
	s_barrier
	v_mfma_f32_16x16x32_bf16 v[52:55], v[202:205], v[146:149], v[52:55]
	v_mfma_f32_16x16x32_bf16 v[48:51], v[222:225], v[146:149], v[48:51]
	v_mfma_f32_16x16x32_bf16 v[36:39], v[202:205], v[154:157], v[36:39]
	v_mfma_f32_16x16x32_bf16 v[32:35], v[222:225], v[154:157], v[32:35]
	v_mfma_f32_16x16x32_bf16 v[20:23], v[202:205], v[162:165], v[20:23]
	v_mfma_f32_16x16x32_bf16 v[16:19], v[222:225], v[162:165], v[16:19]
	v_mfma_f32_16x16x32_bf16 v[4:7], v[202:205], v[194:197], v[4:7]
	v_mfma_f32_16x16x32_bf16 v[0:3], v[222:225], v[194:197], v[0:3]
	v_mfma_f32_16x16x32_bf16 v[52:55], v[218:221], v[150:153], v[52:55]
	v_mfma_f32_16x16x32_bf16 v[48:51], v[228:231], v[150:153], v[48:51]
	v_mfma_f32_16x16x32_bf16 v[36:39], v[218:221], v[158:161], v[36:39]
	v_mfma_f32_16x16x32_bf16 v[32:35], v[228:231], v[158:161], v[32:35]
	v_mfma_f32_16x16x32_bf16 v[20:23], v[218:221], v[166:169], v[20:23]
	v_mfma_f32_16x16x32_bf16 v[16:19], v[228:231], v[166:169], v[16:19]
	v_mfma_f32_16x16x32_bf16 v[4:7], v[218:221], v[198:201], v[4:7]
	v_mfma_f32_16x16x32_bf16 v[0:3], v[228:231], v[198:201], v[0:3]
	s_barrier
	s_add_i32 s27, 0, 0x18000
	ds_read_b128 v[128:131], v207 offset:32768
	ds_read_b128 v[132:135], v207 offset:33792
	ds_read_b128 v[136:139], v207 offset:34816
	ds_read_b128 v[140:143], v207 offset:35840
	s_add_u32 s44, s44, s98
	s_addc_u32 s45, s45, 0
	s_mov_b32 m0, s87
	ds_read_b128 v[146:149], v217 offset:32768
	ds_read_b128 v[150:153], v217 offset:33792
	ds_read_b128 v[154:157], v217 offset:34816
	ds_read_b128 v[158:161], v217 offset:35840
	ds_read_b128 v[162:165], v217 offset:36864
	ds_read_b128 v[166:169], v217 offset:37888
	ds_read_b128 v[194:197], v217 offset:38912
	ds_read_b128 v[198:201], v217 offset:39936
	global_load_lds_dwordx4 v144, s[44:45]
	s_mov_b32 m0, s80
	s_nop 0
	global_load_lds_dwordx4 v188, s[44:45]
	s_waitcnt lgkmcnt(8)
	s_barrier
	s_waitcnt lgkmcnt(0)
	v_mfma_f32_16x16x32_bf16 v[124:127], v[128:131], v[146:149], v[124:127]
	v_mfma_f32_16x16x32_bf16 v[120:123], v[136:139], v[146:149], v[120:123]
	v_mfma_f32_16x16x32_bf16 v[108:111], v[128:131], v[154:157], v[108:111]
	v_mfma_f32_16x16x32_bf16 v[104:107], v[136:139], v[154:157], v[104:107]
	v_mfma_f32_16x16x32_bf16 v[92:95], v[128:131], v[162:165], v[92:95]
	v_mfma_f32_16x16x32_bf16 v[88:91], v[136:139], v[162:165], v[88:91]
	v_mfma_f32_16x16x32_bf16 v[76:79], v[128:131], v[194:197], v[76:79]
	v_mfma_f32_16x16x32_bf16 v[72:75], v[136:139], v[194:197], v[72:75]
	v_mfma_f32_16x16x32_bf16 v[124:127], v[132:135], v[150:153], v[124:127]
	v_mfma_f32_16x16x32_bf16 v[120:123], v[140:143], v[150:153], v[120:123]
	v_mfma_f32_16x16x32_bf16 v[108:111], v[132:135], v[158:161], v[108:111]
	v_mfma_f32_16x16x32_bf16 v[104:107], v[140:143], v[158:161], v[104:107]
	v_mfma_f32_16x16x32_bf16 v[92:95], v[132:135], v[166:169], v[92:95]
	v_mfma_f32_16x16x32_bf16 v[88:91], v[140:143], v[166:169], v[88:91]
	v_mfma_f32_16x16x32_bf16 v[76:79], v[132:135], v[198:201], v[76:79]
	v_mfma_f32_16x16x32_bf16 v[72:75], v[140:143], v[198:201], v[72:75]
	s_barrier
	s_add_i32 s44, 0, 0x1c000
	s_add_i32 s27, s27, s84
	s_add_u32 s100, s78, s18
	s_addc_u32 s101, s79, s19
	s_mov_b32 m0, s27
	ds_read_b128 v[202:205], v207 offset:49152
	ds_read_b128 v[218:221], v207 offset:50176
	ds_read_b128 v[222:225], v207 offset:51200
	ds_read_b128 v[228:231], v207 offset:52224
	global_load_lds_dwordx4 v144, s[100:101]
	s_add_u32 s100, s78, s18
	s_addc_u32 s101, s79, s19
	s_add_i32 m0, s27, 0x2000
	s_nop 0
	global_load_lds_dwordx4 v188, s[100:101]
	s_barrier
	s_waitcnt lgkmcnt(0)
	v_mfma_f32_16x16x32_bf16 v[116:119], v[202:205], v[146:149], v[116:119]
	v_mfma_f32_16x16x32_bf16 v[112:115], v[222:225], v[146:149], v[112:115]
	v_mfma_f32_16x16x32_bf16 v[100:103], v[202:205], v[154:157], v[100:103]
	v_mfma_f32_16x16x32_bf16 v[96:99], v[222:225], v[154:157], v[96:99]
	v_mfma_f32_16x16x32_bf16 v[84:87], v[202:205], v[162:165], v[84:87]
	v_mfma_f32_16x16x32_bf16 v[80:83], v[222:225], v[162:165], v[80:83]
	v_mfma_f32_16x16x32_bf16 v[68:71], v[202:205], v[194:197], v[68:71]
	v_mfma_f32_16x16x32_bf16 v[64:67], v[222:225], v[194:197], v[64:67]
	v_mfma_f32_16x16x32_bf16 v[116:119], v[218:221], v[150:153], v[116:119]
	v_mfma_f32_16x16x32_bf16 v[112:115], v[228:231], v[150:153], v[112:115]
	v_mfma_f32_16x16x32_bf16 v[100:103], v[218:221], v[158:161], v[100:103]
	v_mfma_f32_16x16x32_bf16 v[96:99], v[228:231], v[158:161], v[96:99]
	v_mfma_f32_16x16x32_bf16 v[84:87], v[218:221], v[166:169], v[84:87]
	v_mfma_f32_16x16x32_bf16 v[80:83], v[228:231], v[166:169], v[80:83]
	v_mfma_f32_16x16x32_bf16 v[68:71], v[218:221], v[198:201], v[68:71]
	v_mfma_f32_16x16x32_bf16 v[64:67], v[228:231], v[198:201], v[64:67]
	s_barrier
	s_mov_b32 m0, s30
	v_lshl_add_u64 v[176:177], v[234:235], 0, s[18:19]
	ds_read_b128 v[146:149], v217 offset:49152
	ds_read_b128 v[150:153], v217 offset:50176
	ds_read_b128 v[154:157], v217 offset:51200
	ds_read_b128 v[158:161], v217 offset:52224
	ds_read_b128 v[162:165], v217 offset:53248
	ds_read_b128 v[166:169], v217 offset:54272
	ds_read_b128 v[194:197], v217 offset:55296
	ds_read_b128 v[198:201], v217 offset:56320
	global_load_lds_dwordx4 v[176:177], off
	v_lshl_add_u64 v[176:177], v[236:237], 0, s[18:19]
	s_mov_b32 m0, s31
	s_nop 0
	global_load_lds_dwordx4 v[176:177], off
	s_barrier
	s_waitcnt lgkmcnt(0)
	v_mfma_f32_16x16x32_bf16 v[60:63], v[128:131], v[146:149], v[60:63]
	v_mfma_f32_16x16x32_bf16 v[56:59], v[136:139], v[146:149], v[56:59]
	v_mfma_f32_16x16x32_bf16 v[44:47], v[128:131], v[154:157], v[44:47]
	v_mfma_f32_16x16x32_bf16 v[40:43], v[136:139], v[154:157], v[40:43]
	v_mfma_f32_16x16x32_bf16 v[28:31], v[128:131], v[162:165], v[28:31]
	v_mfma_f32_16x16x32_bf16 v[24:27], v[136:139], v[162:165], v[24:27]
	v_mfma_f32_16x16x32_bf16 v[12:15], v[128:131], v[194:197], v[12:15]
	v_mfma_f32_16x16x32_bf16 v[8:11], v[136:139], v[194:197], v[8:11]
	v_mfma_f32_16x16x32_bf16 v[60:63], v[132:135], v[150:153], v[60:63]
	v_mfma_f32_16x16x32_bf16 v[56:59], v[140:143], v[150:153], v[56:59]
	v_mfma_f32_16x16x32_bf16 v[44:47], v[132:135], v[158:161], v[44:47]
	v_mfma_f32_16x16x32_bf16 v[40:43], v[140:143], v[158:161], v[40:43]
	v_mfma_f32_16x16x32_bf16 v[28:31], v[132:135], v[166:169], v[28:31]
	v_mfma_f32_16x16x32_bf16 v[24:27], v[140:143], v[166:169], v[24:27]
	v_mfma_f32_16x16x32_bf16 v[12:15], v[132:135], v[198:201], v[12:15]
	v_mfma_f32_16x16x32_bf16 v[8:11], v[140:143], v[198:201], v[8:11]
	s_barrier
	s_add_i32 s27, s44, s84
	s_add_u32 s100, s58, s18
	s_addc_u32 s101, s59, s19
	s_mov_b32 m0, s27
	s_nop 0
	global_load_lds_dwordx4 v144, s[100:101]
	s_add_u32 s100, s58, s18
	s_addc_u32 s101, s59, s19
	s_add_i32 m0, s27, 0x2000
	s_nop 0
	global_load_lds_dwordx4 v188, s[100:101]
	s_waitcnt vmcnt(6)
	s_barrier
	v_mfma_f32_16x16x32_bf16 v[52:55], v[202:205], v[146:149], v[52:55]
	v_mfma_f32_16x16x32_bf16 v[48:51], v[222:225], v[146:149], v[48:51]
	v_mfma_f32_16x16x32_bf16 v[36:39], v[202:205], v[154:157], v[36:39]
	v_mfma_f32_16x16x32_bf16 v[32:35], v[222:225], v[154:157], v[32:35]
	v_mfma_f32_16x16x32_bf16 v[20:23], v[202:205], v[162:165], v[20:23]
	v_mfma_f32_16x16x32_bf16 v[16:19], v[222:225], v[162:165], v[16:19]
	v_mfma_f32_16x16x32_bf16 v[4:7], v[202:205], v[194:197], v[4:7]
	v_mfma_f32_16x16x32_bf16 v[0:3], v[222:225], v[194:197], v[0:3]
	v_mfma_f32_16x16x32_bf16 v[52:55], v[218:221], v[150:153], v[52:55]
	v_mfma_f32_16x16x32_bf16 v[48:51], v[228:231], v[150:153], v[48:51]
	v_mfma_f32_16x16x32_bf16 v[36:39], v[218:221], v[158:161], v[36:39]
	v_mfma_f32_16x16x32_bf16 v[32:35], v[228:231], v[158:161], v[32:35]
	v_mfma_f32_16x16x32_bf16 v[20:23], v[218:221], v[166:169], v[20:23]
	v_mfma_f32_16x16x32_bf16 v[16:19], v[228:231], v[166:169], v[16:19]
	v_mfma_f32_16x16x32_bf16 v[4:7], v[218:221], v[198:201], v[4:7]
	v_mfma_f32_16x16x32_bf16 v[0:3], v[228:231], v[198:201], v[0:3]
	s_barrier
	s_add_u32 s42, s42, 0x100
	s_addc_u32 s43, s43, 0
	s_add_u32 s33, s33, 0x100
	s_addc_u32 s37, s37, 0
	s_cmp_ge_u32 s56, s34
	s_mov_b32 s27, s56
	s_cbranch_scc0 .LBB0_196
	v_lshl_add_u32 v194, s11, 8, v206
	v_ashrrev_i32_e32 v195, 31, v194
	v_lshl_or_b32 v196, s10, 8, v216
	v_lshlrev_b64 v[128:129], 11, v[194:195]
	v_ashrrev_i32_e32 v197, 31, v196
	s_and_b64 vcc, exec, s[92:93]
	v_or_b32_e32 v198, 16, v194
	v_lshl_add_u64 v[200:201], s[54:55], 0, v[128:129]
	s_cbranch_vccz .LBB0_215
	v_lshlrev_b64 v[128:129], 12, v[194:195]
	v_lshl_add_u64 v[128:129], s[50:51], 0, v[128:129]
	v_lshlrev_b64 v[130:131], 2, v[196:197]
	v_lshl_add_u64 v[128:129], v[128:129], 0, v[130:131]
	global_load_dwordx4 v[146:149], v[128:129], off offset:16
	global_load_dwordx4 v[150:153], v[128:129], off
	global_load_dwordx4 v[154:157], v[128:129], off offset:528
	global_load_dwordx4 v[158:161], v[128:129], off offset:512
	v_ashrrev_i32_e32 v199, 31, v198
	v_lshlrev_b64 v[128:129], 12, v[198:199]
	v_lshl_add_u64 v[128:129], s[50:51], 0, v[128:129]
	v_lshl_add_u64 v[132:133], v[128:129], 0, v[130:131]
	global_load_dwordx4 v[136:139], v[132:133], off offset:16
	global_load_dwordx4 v[140:143], v[132:133], off
	global_load_dwordx4 v[128:131], v[132:133], off offset:528
	s_nop 0
	global_load_dwordx4 v[132:135], v[132:133], off offset:512
	v_lshl_add_u64 v[166:167], v[196:197], 1, v[200:201]
	s_waitcnt vmcnt(0)
	v_pk_add_f32 v[164:165], v[120:121], v[146:147]
	v_pk_add_f32 v[152:153], v[126:127], v[152:153]
	v_pk_add_f32 v[150:151], v[124:125], v[150:151]
	v_pk_add_f32 v[162:163], v[122:123], v[148:149]
	v_cvt_pk_bf16_f32 v146, v150, v151
	v_cvt_pk_bf16_f32 v147, v152, v153
	v_cvt_pk_bf16_f32 v148, v164, v165
	v_pk_add_f32 v[156:157], v[114:115], v[156:157]
	v_cvt_pk_bf16_f32 v149, v162, v163
	global_store_dwordx4 v[166:167], v[146:149], off
	v_pk_add_f32 v[154:155], v[112:113], v[154:155]
	s_nop 0
	v_mul_f32_e32 v146, v151, v151
	v_mul_f32_e32 v147, v153, v153
	v_fmac_f32_e32 v146, v150, v150
	v_fmac_f32_e32 v147, v152, v152
	v_add_f32_e32 v146, v146, v147
	v_mul_f32_e32 v147, v165, v165
	v_mul_f32_e32 v148, v163, v163
	v_fmac_f32_e32 v147, v164, v164
	v_fmac_f32_e32 v148, v162, v162
	v_add_f32_e32 v147, v147, v148
	v_add_f32_e32 v162, v146, v147
	v_pk_add_f32 v[150:151], v[118:119], v[160:161]
	v_pk_add_f32 v[152:153], v[116:117], v[158:159]
	s_nop 0
	v_cvt_pk_bf16_f32 v146, v152, v153
	v_cvt_pk_bf16_f32 v147, v150, v151
	v_cvt_pk_bf16_f32 v148, v154, v155
	v_cvt_pk_bf16_f32 v149, v156, v157
	global_store_dwordx4 v[166:167], v[146:149], off offset:256
	s_nop 1
	v_mul_f32_e32 v146, v153, v153
	v_mul_f32_e32 v147, v151, v151
	v_fmac_f32_e32 v146, v152, v152
	v_fmac_f32_e32 v147, v150, v150
	v_add_f32_e32 v146, v146, v147
	v_mul_f32_e32 v147, v155, v155
	v_mul_f32_e32 v148, v157, v157
	v_fmac_f32_e32 v147, v154, v154
	v_fmac_f32_e32 v148, v156, v156
	v_add_f32_e32 v147, v147, v148
	v_and_b32_e32 v148, 64, v214
	v_add_f32_e32 v146, v146, v147
	v_xor_b32_e32 v147, 16, v214
	v_add_u32_e32 v148, 64, v148
	v_cmp_lt_i32_e32 vcc, v147, v148
	v_add_f32_e32 v146, v162, v146
	s_nop 0
	v_cndmask_b32_e32 v147, v214, v147, vcc
	v_lshlrev_b32_e32 v218, 2, v147
	ds_bpermute_b32 v147, v218, v146
	s_waitcnt lgkmcnt(0)
	v_add_f32_e32 v146, v146, v147
	v_xor_b32_e32 v147, 32, v214
	v_cmp_lt_i32_e32 vcc, v147, v148
	s_nop 1
	v_cndmask_b32_e32 v147, v214, v147, vcc
	v_lshlrev_b32_e32 v219, 2, v147
	ds_bpermute_b32 v147, v219, v146
	s_and_saveexec_b64 s[42:43], s[38:39]
	s_cbranch_execz .LBB0_200
	s_waitcnt lgkmcnt(0)
	v_add_f32_e32 v146, v146, v147
	v_fma_f32 v146, v146, s91, 0.5
	v_trunc_f32_e32 v146, v146
	v_mul_f32_e32 v147, 0x2f800000, v146
	v_floor_f32_e32 v147, v147
	v_fmac_f32_e32 v146, 0xcf800000, v147
	v_cvt_u32_f32_e32 v146, v146
	v_cvt_u32_f32_e32 v147, v147
	v_lshl_add_u64 v[148:149], v[194:195], 3, s[52:53]
	global_atomic_add_x2 v[148:149], v[146:147], off
